# GL chunk/diag items: LDS weight reads of gate dot + value conv hoisted (counted waits); HG item P3 read batching; P1 loops unrolled
# speedup vs baseline: 1.0256x; 1.0192x over previous
; #define LAS __attribute__((address_space(3)))
; __device__ __forceinline__ void gl_item_C(const Params& p, int l, int seg, int h, LAS float* sm, int tid, int lane, int wave) {
;     ...
;             for (int t = j; t < TS; ++t) {
;                 const float q0 = nq0, q1 = nq1, q2 = nq2, d0 = nd0, d1 = nd1, d2 = nd2;
;                 { const int tn = (t + 1 < TS) ? t + 1 : t, tn2 = (t + 2 < TS) ? t + 2 : TS - 1;
;                   const LAS float* qp = bf + tn * K + 3 * sl; nq0 = qp[0]; nq1 = qp[1]; nq2 = qp[2];
;                   const LAS float* dp = bf + 2048 + tn2 * K + 3 * sl; nd0 = dp[0]; nd1 = dp[1]; nd2 = dp[2]; }
;                 part[(t * 16 + j) * 16 + sl] = q0 * z0 + q1 * z1 + q2 * z2;
;                 z0 *= d0; z1 *= d1; z2 *= d2;
;             }
.LBB0_339:
	v_min_i32_e32 v53, 13, v210
	v_cmp_ne_u32_e32 vcc, 15, v210
	v_mov_b32_e32 v59, 0x2d0
	s_nop 0
	v_cndmask_b32_e32 v59, v59, v208, vcc
	v_mad_u64_u32 v[214:215], vcc, v53, s86, v[0:1]
	v_lshl_add_u32 v59, v59, 2, v0
	v_add_u32_e32 v53, 0x2180, v214
	ds_read2_b32 v[246:247], v59 offset1:1
	ds_read_b32 v248, v59 offset:8
	ds_read2_b32 v[250:251], v53 offset1:1
	ds_read_b32 v252, v214 offset:8584
	s_waitcnt lgkmcnt(4)
	v_mov_b32_e32 v53, v50
	v_mov_b32_e32 v59, v62
	v_pk_mul_f32 v[58:59], v[52:53], v[58:59]
	v_cmp_lt_i32_e32 vcc, 14, v210
	v_fma_f32 v53, v51, v63, v59
	v_add_f32_e32 v53, v58, v53
	ds_write_b32 v209, v53
	v_pk_mul_f32 v[50:51], v[50:51], v[60:61]
	v_mul_f32_e32 v52, v52, v211
	v_add_u32_e32 v209, 0x400, v209
	v_add_u32_e32 v208, 48, v208
	v_add_u32_e32 v210, 1, v210
	s_or_b64 s[40:41], vcc, s[40:41]
	s_andn2_b64 exec, exec, s[40:41]
	s_cbranch_execz .Lmy_glp1_done
	v_min_i32_e32 v53, 13, v210
	v_cmp_ne_u32_e32 vcc, 15, v210
	v_mov_b32_e32 v212, 0x2d0
	s_nop 0
	v_cndmask_b32_e32 v212, v212, v208, vcc
	v_mad_u64_u32 v[214:215], vcc, v53, s86, v[0:1]
	v_lshl_add_u32 v212, v212, 2, v0
	v_add_u32_e32 v53, 0x2180, v214
	ds_read2_b32 v[62:63], v212 offset1:1
	ds_read_b32 v58, v212 offset:8
	ds_read2_b32 v[60:61], v53 offset1:1
	ds_read_b32 v211, v214 offset:8584
	s_waitcnt lgkmcnt(4)
	v_mov_b32_e32 v53, v50
	v_mov_b32_e32 v249, v246
	v_pk_mul_f32 v[248:249], v[52:53], v[248:249]
	v_cmp_lt_i32_e32 vcc, 14, v210
	v_fma_f32 v53, v51, v247, v249
	v_add_f32_e32 v53, v248, v53
	ds_write_b32 v209, v53
	v_pk_mul_f32 v[50:51], v[50:51], v[250:251]
	v_mul_f32_e32 v52, v52, v252
	v_add_u32_e32 v209, 0x400, v209
	v_add_u32_e32 v208, 48, v208
	v_add_u32_e32 v210, 1, v210
	s_or_b64 s[40:41], vcc, s[40:41]
	s_andn2_b64 exec, exec, s[40:41]
	s_cbranch_execnz .LBB0_339
.Lmy_glp1_done:
.LBB0_340:
	s_or_b64 exec, exec, s[38:39]

.LBB0_359:
	s_xor_b32 s0, s4, 1
	s_mulk_i32 s0, 0x7800
	s_add_i32 s0, s0, 0
	v_lshl_add_u32 v0, v54, 2, s0
	s_and_saveexec_b64 s[34:35], s[10:11]
	s_cbranch_execz .LBB0_361
	ds_read_b32 v209, v137
	ds_read_b32 v211, v138
	v_lshlrev_b32_e32 v210, 16, v18
	ds_read_b32 v30, v125
	ds_read_b32 v48, v126
	ds_read_b32 v50, v127
	ds_read_b32 v52, v128
	ds_read_b32 v58, v129
	ds_read_b32 v60, v134
	ds_read_b32 v62, v135
	ds_read_b32 v163, v136
	ds_read_b32 v212, v139
	ds_read_b32 v213, v140
	ds_read_b32 v214, v141
	ds_read_b32 v215, v142
	ds_read_b32 v216, v143
	s_waitcnt lgkmcnt(5)
	ds_read_b32 v217, v144
	ds_read_b32 v218, v145
	ds_read_b32 v245, v146
	ds_read_b32 v246, v147
	ds_read_b32 v247, v148
	ds_read_b32 v248, v149
	ds_read_b32 v249, v150
	ds_read_b32 v250, v151
	ds_read_b32 v251, v152
	ds_read_b32 v252, v153
	v_fmac_f32_e32 v209, v211, v210
	v_and_b32_e32 v210, 0xffff0000, v18
	v_lshlrev_b32_e32 v32, 16, v64
	v_lshlrev_b32_e32 v49, 16, v57
	v_fma_f32 v30, v30, v32, 0
	s_waitcnt lgkmcnt(14)
	v_fmac_f32_e32 v209, v212, v210
	v_lshlrev_b32_e32 v210, 16, v19
	v_fma_f32 v32, v48, v49, 0
	v_lshlrev_b32_e32 v51, 16, v66
	v_fmac_f32_e32 v30, v50, v51
	s_waitcnt lgkmcnt(13)
	v_fmac_f32_e32 v209, v213, v210
	v_and_b32_e32 v210, 0xffff0000, v19
	v_lshlrev_b32_e32 v59, 16, v68
	v_lshlrev_b32_e32 v63, 16, v70
	v_fmac_f32_e32 v30, v58, v59
	s_waitcnt lgkmcnt(12)
	v_fmac_f32_e32 v209, v214, v210
	v_lshlrev_b32_e32 v210, 16, v20
	v_fmac_f32_e32 v30, v62, v63
	v_lshlrev_b32_e32 v53, 16, v65
	v_lshlrev_b32_e32 v61, 16, v67
	s_waitcnt lgkmcnt(11)
	v_fmac_f32_e32 v209, v215, v210
	v_and_b32_e32 v210, 0xffff0000, v20
	v_fmac_f32_e32 v32, v52, v53
	v_lshlrev_b32_e32 v208, 16, v69
	v_fmac_f32_e32 v32, v60, v61
	s_waitcnt lgkmcnt(10)
	v_fmac_f32_e32 v209, v216, v210
	v_lshlrev_b32_e32 v210, 16, v21
	v_fmac_f32_e32 v32, v163, v208
	s_waitcnt lgkmcnt(9)
	v_fmac_f32_e32 v209, v217, v210
	v_and_b32_e32 v210, 0xffff0000, v21
	s_waitcnt lgkmcnt(8)
	v_fmac_f32_e32 v209, v218, v210
	v_lshlrev_b32_e32 v210, 16, v14
	s_waitcnt lgkmcnt(7)
	v_fmac_f32_e32 v209, v245, v210
	v_and_b32_e32 v210, 0xffff0000, v14
	s_waitcnt lgkmcnt(6)
	v_fmac_f32_e32 v209, v246, v210
	v_lshlrev_b32_e32 v210, 16, v15
	s_waitcnt lgkmcnt(5)
	v_fmac_f32_e32 v209, v247, v210
	v_and_b32_e32 v210, 0xffff0000, v15
	s_waitcnt lgkmcnt(4)
	v_fmac_f32_e32 v209, v248, v210
	v_lshlrev_b32_e32 v210, 16, v16
	s_waitcnt lgkmcnt(3)
	v_fmac_f32_e32 v209, v249, v210
	v_and_b32_e32 v210, 0xffff0000, v16
	s_waitcnt lgkmcnt(2)
	v_fmac_f32_e32 v209, v250, v210
	v_lshlrev_b32_e32 v210, 16, v17
	s_waitcnt lgkmcnt(1)
	v_fmac_f32_e32 v209, v251, v210
	v_and_b32_e32 v210, 0xffff0000, v17
	s_waitcnt lgkmcnt(0)
	v_fmac_f32_e32 v209, v252, v210
	v_mul_f32_e64 v49, |v209|, s48
	v_exp_f32_e32 v49, v49
	v_min_f32_e32 v48, 0, v209
	v_add_f32_e32 v49, 1.0, v49
	v_cmp_gt_f32_e32 vcc, s68, v49
	s_nop 1
	v_cndmask_b32_e64 v50, 0, 32, vcc
	v_ldexp_f32 v49, v49, v50
	v_log_f32_e32 v49, v49
	s_nop 0
	v_mul_f32_e32 v50, 0x3f317217, v49
	v_fma_f32 v50, v49, s42, -v50
	v_fmac_f32_e32 v50, 0x3377d1cf, v49
	v_fmac_f32_e32 v50, 0x3f317217, v49
	v_cmp_lt_f32_e64 s[0:1], |v49|, s78
	s_nop 1
	v_cndmask_b32_e64 v49, v49, v50, s[0:1]
	v_cndmask_b32_e32 v50, 0, v164, vcc
	v_sub_f32_e32 v49, v49, v50
	v_sub_f32_e32 v48, v48, v49
	v_mul_f32_e32 v49, 0xbfb8aa3b, v30
	v_exp_f32_e32 v49, v49
	v_mul_f32_e32 v48, 0x3d800000, v48
	v_mul_f32_e32 v48, 0x3fb8aa3b, v48
	v_exp_f32_e32 v48, v48
	v_add_f32_e32 v49, 1.0, v49
	v_rcp_f32_e32 v49, v49
	s_nop 0
	v_mul_f32_e32 v30, v30, v49
	ds_write_b32 v0, v30 offset:16384
	v_mul_f32_e32 v30, 0xbfb8aa3b, v32
	v_exp_f32_e32 v30, v30
	s_nop 0
	v_add_f32_e32 v30, 1.0, v30
	v_rcp_f32_e32 v30, v30
	s_nop 0
	v_mul_f32_e32 v30, v32, v30
	v_mul_f32_e32 v30, 0x3e13cd3a, v30
	ds_write2st64_b32 v0, v30, v48 offset1:32
.LBB0_361:
	s_or_b64 exec, exec, s[34:35]
	s_and_saveexec_b64 s[34:35], s[14:15]
	s_cbranch_execz .LBB0_363
	ds_read_b32 v209, v178
	ds_read_b32 v211, v179
	v_lshlrev_b32_e32 v210, 16, v26
	ds_read_b32 v30, v155
	ds_read_b32 v48, v156
	ds_read_b32 v50, v157
	ds_read_b32 v52, v158
	ds_read_b32 v58, v159
	ds_read_b32 v60, v175
	ds_read_b32 v62, v176
	ds_read_b32 v163, v177
	ds_read_b32 v212, v182
	ds_read_b32 v213, v183
	ds_read_b32 v214, v184
	ds_read_b32 v215, v185
	ds_read_b32 v216, v186
	s_waitcnt lgkmcnt(5)
	ds_read_b32 v217, v187
	ds_read_b32 v218, v188
	ds_read_b32 v245, v189
	ds_read_b32 v246, v190
	ds_read_b32 v247, v191
	ds_read_b32 v248, v192
	ds_read_b32 v249, v193
	ds_read_b32 v250, v194
	ds_read_b32 v251, v195
	ds_read_b32 v252, v196
	v_fmac_f32_e32 v209, v211, v210
	v_and_b32_e32 v210, 0xffff0000, v26
	v_lshlrev_b32_e32 v32, 16, v72
	v_lshlrev_b32_e32 v49, 16, v71
	v_fma_f32 v30, v30, v32, 0
	s_waitcnt lgkmcnt(14)
	v_fmac_f32_e32 v209, v212, v210
	v_lshlrev_b32_e32 v210, 16, v27
	v_fma_f32 v32, v48, v49, 0
	v_lshlrev_b32_e32 v51, 16, v74
	v_fmac_f32_e32 v30, v50, v51
	s_waitcnt lgkmcnt(13)
	v_fmac_f32_e32 v209, v213, v210
	v_and_b32_e32 v210, 0xffff0000, v27
	v_lshlrev_b32_e32 v59, 16, v77
	v_lshlrev_b32_e32 v63, 16, v80
	v_fmac_f32_e32 v30, v58, v59
	s_waitcnt lgkmcnt(12)
	v_fmac_f32_e32 v209, v214, v210
	v_lshlrev_b32_e32 v210, 16, v28
	v_fmac_f32_e32 v30, v62, v63
	v_lshlrev_b32_e32 v53, 16, v73
	v_lshlrev_b32_e32 v61, 16, v76
	s_waitcnt lgkmcnt(11)
	v_fmac_f32_e32 v209, v215, v210
	v_and_b32_e32 v210, 0xffff0000, v28
	v_fmac_f32_e32 v32, v52, v53
	v_lshlrev_b32_e32 v208, 16, v79
	v_fmac_f32_e32 v32, v60, v61
	s_waitcnt lgkmcnt(10)
	v_fmac_f32_e32 v209, v216, v210
	v_lshlrev_b32_e32 v210, 16, v29
	v_fmac_f32_e32 v32, v163, v208
	s_waitcnt lgkmcnt(9)
	v_fmac_f32_e32 v209, v217, v210
	v_and_b32_e32 v210, 0xffff0000, v29
	s_waitcnt lgkmcnt(8)
	v_fmac_f32_e32 v209, v218, v210
	v_lshlrev_b32_e32 v210, 16, v22
	s_waitcnt lgkmcnt(7)
	v_fmac_f32_e32 v209, v245, v210
	v_and_b32_e32 v210, 0xffff0000, v22
	s_waitcnt lgkmcnt(6)
	v_fmac_f32_e32 v209, v246, v210
	v_lshlrev_b32_e32 v210, 16, v23
	s_waitcnt lgkmcnt(5)
	v_fmac_f32_e32 v209, v247, v210
	v_and_b32_e32 v210, 0xffff0000, v23
	s_waitcnt lgkmcnt(4)
	v_fmac_f32_e32 v209, v248, v210
	v_lshlrev_b32_e32 v210, 16, v24
	s_waitcnt lgkmcnt(3)
	v_fmac_f32_e32 v209, v249, v210
	v_and_b32_e32 v210, 0xffff0000, v24
	s_waitcnt lgkmcnt(2)
	v_fmac_f32_e32 v209, v250, v210
	v_lshlrev_b32_e32 v210, 16, v25
	s_waitcnt lgkmcnt(1)
	v_fmac_f32_e32 v209, v251, v210
	v_and_b32_e32 v210, 0xffff0000, v25
	s_waitcnt lgkmcnt(0)
	v_fmac_f32_e32 v209, v252, v210
	v_mul_f32_e64 v49, |v209|, s48
	v_exp_f32_e32 v49, v49
	v_min_f32_e32 v48, 0, v209
	v_add_f32_e32 v49, 1.0, v49
	v_cmp_gt_f32_e32 vcc, s68, v49
	s_nop 1
	v_cndmask_b32_e64 v50, 0, 32, vcc
	v_ldexp_f32 v49, v49, v50
	v_log_f32_e32 v49, v49
	s_nop 0
	v_mul_f32_e32 v50, 0x3f317217, v49
	v_fma_f32 v50, v49, s42, -v50
	v_fmac_f32_e32 v50, 0x3377d1cf, v49
	v_fmac_f32_e32 v50, 0x3f317217, v49
	v_cmp_lt_f32_e64 s[0:1], |v49|, s78
	s_nop 1
	v_cndmask_b32_e64 v49, v49, v50, s[0:1]
	v_cndmask_b32_e32 v50, 0, v164, vcc
	v_sub_f32_e32 v49, v49, v50
	v_sub_f32_e32 v48, v48, v49
	v_mul_f32_e32 v49, 0xbfb8aa3b, v30
	v_exp_f32_e32 v49, v49
	v_mul_f32_e32 v48, 0x3d800000, v48
	v_mul_f32_e32 v48, 0x3fb8aa3b, v48
	v_exp_f32_e32 v48, v48
	v_add_f32_e32 v49, 1.0, v49
	v_rcp_f32_e32 v49, v49
	s_nop 0
	v_mul_f32_e32 v30, v30, v49
	ds_write_b32 v0, v30 offset:18432
	v_mul_f32_e32 v30, 0xbfb8aa3b, v32
	v_exp_f32_e32 v30, v30
	s_nop 0
	v_add_f32_e32 v30, 1.0, v30
	v_rcp_f32_e32 v30, v30
	s_nop 0
	v_mul_f32_e32 v30, v32, v30
	v_mul_f32_e32 v30, 0x3e13cd3a, v30
	ds_write2st64_b32 v0, v30, v48 offset0:8 offset1:40
.LBB0_363:
	s_or_b64 exec, exec, s[34:35]
	ds_read_b32 v212, v83
	ds_read_b32 v213, v84
	ds_read_b32 v214, v85
	ds_read_b32 v215, v86
	ds_read_b32 v216, v87
	ds_read_b32 v217, v88
	ds_read_b32 v218, v89
	ds_read_b32 v245, v90
	ds_read_b32 v246, v91
	ds_read_b32 v247, v92
	ds_read_b32 v248, v93
	ds_read_b32 v249, v94
	v_lshlrev_b32_e32 v32, 16, v108
	v_lshlrev_b32_e32 v48, 16, v107
	s_waitcnt lgkmcnt(11)
	v_fma_f32 v30, v212, v32, 0
	s_waitcnt lgkmcnt(10)
	v_fmac_f32_e32 v30, v213, v48
	v_lshlrev_b32_e32 v48, 16, v122
	s_waitcnt lgkmcnt(9)
	v_fmac_f32_e32 v30, v214, v48
	v_lshlrev_b32_e32 v48, 16, v119
	s_waitcnt lgkmcnt(8)
	v_fmac_f32_e32 v30, v215, v48
	v_mul_f32_e32 v32, 0xbfb8aa3b, v30
	v_exp_f32_e32 v32, v32
	v_lshlrev_b32_e32 v48, 16, v180
	v_add_f32_e32 v32, 1.0, v32
	v_rcp_f32_e32 v32, v32
	s_nop 0
	v_mul_f32_e32 v30, v30, v32
	ds_write_b32 v0, v30 offset:24576
	v_lshlrev_b32_e32 v32, 16, v181
	s_waitcnt lgkmcnt(8)
	v_fma_f32 v30, v216, v32, 0
	s_waitcnt lgkmcnt(7)
	v_fmac_f32_e32 v30, v217, v48
	v_lshlrev_b32_e32 v48, 16, v203
	s_waitcnt lgkmcnt(6)
	v_fmac_f32_e32 v30, v218, v48
	v_lshlrev_b32_e32 v48, 16, v202
	s_waitcnt lgkmcnt(5)
	v_fmac_f32_e32 v30, v245, v48
	v_mul_f32_e32 v32, 0xbfb8aa3b, v30
	v_exp_f32_e32 v32, v32
	v_lshlrev_b32_e32 v48, 16, v204
	v_add_f32_e32 v32, 1.0, v32
	v_rcp_f32_e32 v32, v32
	s_nop 0
	v_mul_f32_e32 v30, v30, v32
	ds_write_b32 v0, v30 offset:26624
	v_lshlrev_b32_e32 v32, 16, v205
	s_waitcnt lgkmcnt(5)
	v_fma_f32 v30, v246, v32, 0
	s_waitcnt lgkmcnt(4)
	v_fmac_f32_e32 v30, v247, v48
	v_lshlrev_b32_e32 v48, 16, v207
	s_waitcnt lgkmcnt(3)
	v_fmac_f32_e32 v30, v248, v48
	v_lshlrev_b32_e32 v48, 16, v206
	s_waitcnt lgkmcnt(2)
	v_fmac_f32_e32 v30, v249, v48
	v_mul_f32_e32 v32, 0xbfb8aa3b, v30
	v_exp_f32_e32 v32, v32
	s_nop 0
	v_add_f32_e32 v32, 1.0, v32
	v_rcp_f32_e32 v32, v32
	s_nop 0
	v_mul_f32_e32 v30, v30, v32
	ds_write_b32 v0, v30 offset:28672
	s_cmp_gt_u32 s65, 5
	s_cbranch_scc1 .LBB0_323

; #define LAS __attribute__((address_space(3)))
; __device__ __forceinline__ float bf2f(bf16_t b) { return __uint_as_float(((unsigned)b) << 16); }
; __device__ __forceinline__ bf16_t f2bf(float f) { unsigned u = __float_as_uint(f); u += 0x7FFFu + ((u >> 16) & 1u); return (bf16_t)(u >> 16); }
; __device__ __forceinline__ unsigned pk2(float lo, float hi) { return pg8::cvt_pk_bf16(lo, hi); }
; __device__ __forceinline__ float silu(float x) { return x * __builtin_amdgcn_rcpf(1.0f + __expf(-x)); }
; __device__ __forceinline__ void hg_item_C(const Params& p, int l, int seg, int h, LAS float* sm, int tid, int lane, int wave) {
;     ...
;         if (wave < 4) {
;             f32x4 o = {0.f, 0.f, 0.f, 0.f};
; #pragma unroll
;             for (int kc = 0; kc < 4; ++kc)
;                 o = __builtin_amdgcn_mfma_f32_16x16x32_bf16(*(const LAS pg8::bf16x8*)(qG + row * QP + 32 * kc + 8 * q), *(const LAS pg8::bf16x8*)(Sb + (16 * wave + row) * SP + 32 * kc + 8 * q), o, 0, 0, 0);
;             o = __builtin_amdgcn_mfma_f32_16x16x32_bf16(*(const LAS pg8::bf16x8*)(Am + row * TP + 8 * q), *(const LAS pg8::bf16x8*)(vT + (16 * wave + row) * TP + 8 * q), o, 0, 0, 0);
; #pragma unroll
;             for (int i = 0; i < 4; ++i) ob[(4 * q + i) * 64 + 16 * wave + row] = o[i];
;         }
;         {
;             const f32x4 gg = *(const LAS f32x4*)(G15 + 16 * wave + 4 * q);
;             const pg8::bf16x8 a = *(const LAS pg8::bf16x8*)(kT + (16 * wave + row) * TP + 8 * q);
; #pragma unroll
;             for (int n = 0; n < 4; ++n) S[n] = __builtin_amdgcn_mfma_f32_16x16x32_bf16(a, *(const LAS pg8::bf16x8*)(vT + (16 * n + row) * TP + 8 * q), S[n] * gg, 0, 0, 0);
;         }
;         lds_barrier();
; #pragma unroll
;         for (int n = 0; n < 4; ++n) { u32x2 w; w.x = pk2(S[n][0], S[n][1]); w.y = pk2(S[n][2], S[n][3]); *(LAS u32x2*)(Sb + (16 * n + row) * SP + 16 * wave + 4 * q) = w; }
; #pragma unroll
;         for (int rr = 0; rr < 2; ++rr) {
;             const int t = wave + 8 * rr, tok = seg * SEG + sb * TS + t;
;             const float y = ob[t * 64 + lane];
;             const float ms = wave_sum(y * y) * (1.0f / 64.0f);
;             const float yn = y * rsqrtf(ms + 1e-5f);
;             MX[(size_t)tok * D + 384 + h * 64 + lane] = f2bf(yn * gn1 * silu(bf2f(pf_g1[rr])));
;         }
.LBB0_441:
	s_or_b64 exec, exec, s[18:19]
	s_waitcnt lgkmcnt(0)
	s_barrier
	s_mul_i32 s5, s37, 0xffffa000
	s_add_i32 s4, s4, s5
	s_andn2_b64 vcc, exec, s[16:17]
	s_cbranch_vccnz .LBB0_443
	ds_read_b128 v[20:23], v77
	ds_read_b128 v[24:27], v79
	ds_read_b128 v[176:179], v77 offset:64
	ds_read_b128 v[180:183], v79 offset:64
	ds_read_b128 v[184:187], v77 offset:128
	ds_read_b128 v[188:191], v79 offset:128
	ds_read_b128 v[192:195], v77 offset:192
	ds_read_b128 v[196:199], v79 offset:192
	ds_read_b128 v[200:203], v81
	ds_read_b128 v[204:207], v83
	s_add_i32 s5, s29, s4
	s_waitcnt lgkmcnt(8)
	v_mfma_f32_16x16x32_bf16 v[20:23], v[20:23], v[24:27], 0
	s_waitcnt lgkmcnt(6)
	v_mfma_f32_16x16x32_bf16 v[20:23], v[176:179], v[180:183], v[20:23]
	s_waitcnt lgkmcnt(4)
	v_mfma_f32_16x16x32_bf16 v[20:23], v[184:187], v[188:191], v[20:23]
	s_waitcnt lgkmcnt(2)
	v_mfma_f32_16x16x32_bf16 v[20:23], v[192:195], v[196:199], v[20:23]
	s_waitcnt lgkmcnt(0)
	v_mfma_f32_16x16x32_bf16 v[20:23], v[200:203], v[204:207], v[20:23]
	v_lshlrev_b32_e32 v24, 2, v49
	v_add3_u32 v24, s5, v84, v24
	s_nop 5
	ds_write2st64_b32 v24, v20, v21 offset0:240 offset1:241
	ds_write2st64_b32 v24, v22, v23 offset0:242 offset1:243
.LBB0_443:
	v_add_u32_e32 v28, v82, v80
	ds_read_b128 v[20:23], v85
	ds_read_b128 v[24:27], v86
	ds_read_b128 v[28:31], v28
	ds_read_b128 v[176:179], v101
	ds_read_b128 v[180:183], v101 offset:1280
	ds_read_b128 v[184:187], v102
	s_add_i32 s18, s36, s26
	s_waitcnt lgkmcnt(5)
	v_pk_mul_f32 v[6:7], v[6:7], v[22:23]
	v_pk_mul_f32 v[4:5], v[4:5], v[20:21]
	v_pk_mul_f32 v[10:11], v[10:11], v[22:23]
	v_pk_mul_f32 v[8:9], v[8:9], v[20:21]
	s_waitcnt lgkmcnt(3)
	v_mfma_f32_16x16x32_bf16 v[4:7], v[24:27], v[28:31], v[4:7]
	v_pk_mul_f32 v[14:15], v[14:15], v[22:23]
	v_pk_mul_f32 v[12:13], v[12:13], v[20:21]
	s_waitcnt lgkmcnt(2)
	v_mfma_f32_16x16x32_bf16 v[8:11], v[24:27], v[176:179], v[8:11]
	v_pk_mul_f32 v[18:19], v[18:19], v[22:23]
	v_pk_mul_f32 v[16:17], v[16:17], v[20:21]
	s_waitcnt lgkmcnt(1)
	v_mfma_f32_16x16x32_bf16 v[12:15], v[24:27], v[180:183], v[12:15]
	s_waitcnt lgkmcnt(0)
	s_barrier
	v_cvt_pk_bf16_f32 v20, v4, v5
	v_add_u32_e32 v22, v88, v60
	v_cvt_pk_bf16_f32 v21, v6, v7
	ds_write_b64 v22, v[20:21]
	v_cvt_pk_bf16_f32 v20, v8, v9
	v_cvt_pk_bf16_f32 v21, v10, v11
	ds_write_b64 v22, v[20:21] offset:4352
	v_cvt_pk_bf16_f32 v20, v12, v13
	v_mfma_f32_16x16x32_bf16 v[16:19], v[24:27], v[184:187], v[16:19]
	v_cvt_pk_bf16_f32 v21, v14, v15
	ds_write_b64 v22, v[20:21] offset:8704
	v_cvt_pk_bf16_f32 v20, v16, v17
	v_lshl_add_u32 v22, v56, 2, s4
	v_cvt_pk_bf16_f32 v21, v18, v19
	ds_write_b64 v103, v[20:21]
	v_add_u32_e32 v20, s31, v22
	ds_read_b32 v20, v20 offset:61440
	v_mov_b32_e32 v23, 0
	s_add_i32 s4, s18, s59
	s_add_i32 s18, s18, s34
	s_ashr_i32 s19, s18, 31
	s_waitcnt lgkmcnt(0)
	v_mul_f32_e32 v21, v20, v20
	s_nop 1
	v_mov_b32_dpp v21, v21 quad_perm:[1,0,3,2] row_mask:0xf bank_mask:0xf bound_ctrl:1
	v_fmac_f32_e32 v21, v20, v20
	s_nop 1
	v_add_f32_dpp v21, v21, v21 quad_perm:[2,3,0,1] row_mask:0xf bank_mask:0xf bound_ctrl:1
	s_nop 1
	v_add_f32_dpp v21, v21, v21 row_half_mirror row_mask:0xf bank_mask:0xf bound_ctrl:1
	s_nop 1
	v_add_f32_dpp v21, v21, v21 row_mirror row_mask:0xf bank_mask:0xf bound_ctrl:1
	s_nop 1
	v_mov_b32_dpp v23, v21 row_bcast:15 row_mask:0xa bank_mask:0xf
	v_add_f32_e32 v21, v21, v23
	v_mov_b32_e32 v23, 0
	s_nop 1
	v_mov_b32_dpp v23, v21 row_bcast:31 row_mask:0xc bank_mask:0xf
	v_add_f32_e32 v21, v21, v23
	s_nop 0
	v_readlane_b32 s5, v21, 63
	s_nop 1
	v_fma_f32 v21, s5, v168, v131
	v_cmp_gt_f32_e32 vcc, s68, v21
	v_mul_f32_e32 v23, 0x4b800000, v21
	s_ashr_i32 s5, s4, 31
	v_cndmask_b32_e32 v21, v21, v23, vcc
	v_rsq_f32_e32 v21, v21
	s_lshl_b64 s[4:5], s[4:5], 11
	v_mul_f32_e32 v23, 0x45800000, v21
	v_cndmask_b32_e32 v21, v21, v23, vcc
	v_mul_f32_e32 v20, v20, v21
	s_waitcnt vmcnt(1)
	v_lshlrev_b32_e32 v21, 16, v105
	v_mul_f32_e32 v23, 0xbfb8aa3b, v21
	v_exp_f32_e32 v23, v23
	v_mul_f32_e32 v20, v48, v20
	v_add_f32_e32 v23, 1.0, v23
	v_rcp_f32_e32 v23, v23
	s_nop 0
	v_mul_f32_e32 v21, v23, v21
	v_mul_f32_e32 v20, v21, v20
	v_bfe_u32 v21, v20, 16, 1
	v_add3_u32 v23, v20, v21, s61
	v_lshl_add_u64 v[20:21], v[44:45], 0, s[4:5]
	global_store_short_d16_hi v[20:21], v23, off
	v_add_u32_e32 v20, s35, v22
	ds_read_b32 v20, v20 offset:61440
	v_mov_b32_e32 v22, 0
	s_waitcnt lgkmcnt(0)
	v_mul_f32_e32 v21, v20, v20
	s_nop 1
	v_mov_b32_dpp v21, v21 quad_perm:[1,0,3,2] row_mask:0xf bank_mask:0xf bound_ctrl:1
	v_fmac_f32_e32 v21, v20, v20
	s_nop 1
	v_add_f32_dpp v21, v21, v21 quad_perm:[2,3,0,1] row_mask:0xf bank_mask:0xf bound_ctrl:1
	s_nop 1
	v_add_f32_dpp v21, v21, v21 row_half_mirror row_mask:0xf bank_mask:0xf bound_ctrl:1
	s_nop 1
	v_add_f32_dpp v21, v21, v21 row_mirror row_mask:0xf bank_mask:0xf bound_ctrl:1
	s_nop 1
	v_mov_b32_dpp v22, v21 row_bcast:15 row_mask:0xa bank_mask:0xf
	v_add_f32_e32 v21, v21, v22
	v_mov_b32_e32 v22, 0
	s_nop 1
	v_mov_b32_dpp v22, v21 row_bcast:31 row_mask:0xc bank_mask:0xf
	v_add_f32_e32 v21, v21, v22
	s_nop 0
	v_readlane_b32 s4, v21, 63
	s_nop 1
	v_fma_f32 v21, s4, v168, v131
	v_cmp_gt_f32_e32 vcc, s68, v21
	v_mul_f32_e32 v22, 0x4b800000, v21
	s_lshl_b64 s[4:5], s[18:19], 11
	v_cndmask_b32_e32 v21, v21, v22, vcc
	v_rsq_f32_e32 v21, v21
	s_cmp_eq_u32 s28, 7
	v_mul_f32_e32 v22, 0x45800000, v21
	v_cndmask_b32_e32 v21, v21, v22, vcc
	v_mul_f32_e32 v20, v20, v21
	s_waitcnt vmcnt(1)
	v_lshlrev_b32_e32 v21, 16, v104
	v_mul_f32_e32 v22, 0xbfb8aa3b, v21
	v_exp_f32_e32 v22, v22
	v_mul_f32_e32 v20, v48, v20
	v_add_f32_e32 v22, 1.0, v22
	v_rcp_f32_e32 v22, v22
	s_nop 0
	v_mul_f32_e32 v21, v22, v21
	v_mul_f32_e32 v20, v21, v20
	v_bfe_u32 v21, v20, 16, 1
	v_add3_u32 v22, v20, v21, s61
	v_lshl_add_u64 v[20:21], v[44:45], 0, s[4:5]
	global_store_short_d16_hi v[20:21], v22, off
	s_cbranch_scc1 .LBB0_445
	v_lshlrev_b32_e32 v21, 16, v61
	v_mul_f32_e32 v21, 0xbfb8aa3b, v21
	v_exp_f32_e32 v21, v21
	ds_read_b32 v176, v58
	s_xor_b32 s4, s37, 1
	s_mulk_i32 s4, 0x7800
	v_add_f32_e32 v21, 1.0, v21
	v_rcp_f32_e32 v21, v21
	s_waitcnt lgkmcnt(0)
	v_mov_b32_e32 v22, v176
	v_sub_f32_e32 v23, 1.0, v22
	v_add_u32_e32 v20, s4, v59
	v_fmac_f32_e32 v22, v21, v23
	v_sub_f32_e32 v21, 1.0, v21
	v_mul_f32_e32 v21, v21, v23
	v_max_f32_e32 v22, 0xda24260, v22
	ds_write_b32 v20, v21 offset:16384
	v_lshlrev_b32_e32 v21, 16, v62
	ds_write_b32 v20, v22 offset:8192
	v_mul_f32_e32 v22, 0xbfb8aa3b, v21
	v_exp_f32_e32 v22, v22
	s_nop 0
	v_add_f32_e32 v22, 1.0, v22
	v_rcp_f32_e32 v22, v22
	s_nop 0
	v_mul_f32_e32 v21, v22, v21
	ds_write_b32 v20, v21
	v_lshlrev_b32_e32 v21, 16, v63
	v_mul_f32_e32 v21, 0xbfb8aa3b, v21
	v_exp_f32_e32 v21, v21
	v_mov_b32_e32 v22, v176
	v_add_f32_e32 v21, 1.0, v21
	v_rcp_f32_e32 v21, v21
	v_sub_f32_e32 v23, 1.0, v22
	v_fmac_f32_e32 v22, v21, v23
	v_sub_f32_e32 v21, 1.0, v21
	v_mul_f32_e32 v21, v21, v23
	v_max_f32_e32 v22, 0xda24260, v22
	ds_write_b32 v20, v21 offset:18432
	v_lshlrev_b32_e32 v21, 16, v64
	ds_write_b32 v20, v22 offset:10240
	v_mul_f32_e32 v22, 0xbfb8aa3b, v21
	v_exp_f32_e32 v22, v22
	s_nop 0
	v_add_f32_e32 v22, 1.0, v22
	v_rcp_f32_e32 v22, v22
	s_nop 0
	v_mul_f32_e32 v21, v22, v21
	ds_write_b32 v20, v21 offset:2048
	v_lshlrev_b32_e32 v21, 16, v65
	v_mul_f32_e32 v21, 0xbfb8aa3b, v21
	v_exp_f32_e32 v21, v21
	v_mov_b32_e32 v22, v176
	v_add_f32_e32 v21, 1.0, v21
	v_rcp_f32_e32 v21, v21
	v_sub_f32_e32 v23, 1.0, v22
	v_fmac_f32_e32 v22, v21, v23
	v_sub_f32_e32 v21, 1.0, v21
	v_mul_f32_e32 v21, v21, v23
	v_max_f32_e32 v22, 0xda24260, v22
	ds_write_b32 v20, v21 offset:20480
	v_lshlrev_b32_e32 v21, 16, v66
	ds_write_b32 v20, v22 offset:12288
	v_mul_f32_e32 v22, 0xbfb8aa3b, v21
	v_exp_f32_e32 v22, v22
	s_nop 0
	v_add_f32_e32 v22, 1.0, v22
	v_rcp_f32_e32 v22, v22
	s_nop 0
	v_mul_f32_e32 v21, v22, v21
	ds_write_b32 v20, v21 offset:4096
	v_lshlrev_b32_e32 v21, 16, v74
	v_mul_f32_e32 v21, 0xbfb8aa3b, v21
	v_exp_f32_e32 v21, v21
	v_mov_b32_e32 v22, v176
	v_add_f32_e32 v21, 1.0, v21
	v_rcp_f32_e32 v21, v21
	v_sub_f32_e32 v23, 1.0, v22
	v_fmac_f32_e32 v22, v21, v23
	v_max_f32_e32 v22, 0xda24260, v22
	ds_write_b32 v20, v22 offset:14336
	v_sub_f32_e32 v21, 1.0, v21
	v_lshlrev_b32_e32 v22, 16, v75
	v_mul_f32_e32 v21, v21, v23
	v_mul_f32_e32 v23, 0xbfb8aa3b, v22
	v_exp_f32_e32 v23, v23
	s_nop 0
	v_add_f32_e32 v23, 1.0, v23
	v_rcp_f32_e32 v23, v23
	s_nop 0
	v_mul_f32_e32 v22, v23, v22
	ds_write_b32 v20, v22 offset:6144
	v_lshlrev_b32_e32 v22, 16, v87
	ds_write2st64_b32 v20, v21, v22 offset0:88 offset1:96
	v_lshlrev_b32_e32 v21, 16, v89
	ds_write_b32 v20, v21 offset:26624

.LBB0_648:
	s_mulk_i32 s24, 0x7800
	s_add_i32 s0, s24, 0
	v_lshl_add_u32 v34, v30, 2, s0
	s_and_saveexec_b64 s[24:25], s[10:11]
	s_cbranch_execz .LBB0_650
	ds_read_b32 v141, v121
	ds_read_b32 v147, v124
	ds_read_b32 v149, v125
	s_waitcnt vmcnt(0)
	v_lshlrev_b32_e32 v148, 16, v14
	ds_read_b32 v143, v120
	ds_read_b32 v139, v119
	ds_read_b32 v145, v116
	ds_read_b32 v188, v123
	ds_read_b32 v189, v122
	ds_read_b32 v190, v118
	ds_read_b32 v191, v117
	ds_read_b32 v192, v115
	ds_read_b32 v193, v113
	ds_read_b32 v194, v112
	ds_read_b32 v195, v111
	ds_read_b32 v196, v110
	s_waitcnt lgkmcnt(9)
	ds_read_b32 v197, v108
	ds_read_b32 v198, v105
	ds_read_b32 v199, v104
	ds_read_b32 v200, v103
	ds_read_b32 v201, v102
	ds_read_b32 v202, v101
	v_fmac_f32_e32 v147, v149, v148
	v_and_b32_e32 v148, 0xffff0000, v14
	v_lshlrev_b32_e32 v140, 16, v50
	v_lshlrev_b32_e32 v142, 16, v49
	v_lshlrev_b32_e32 v144, 16, v52
	s_waitcnt lgkmcnt(14)
	v_fmac_f32_e32 v147, v188, v148
	v_lshlrev_b32_e32 v148, 16, v15
	v_lshlrev_b32_e32 v146, 16, v47
	s_waitcnt lgkmcnt(13)
	v_fmac_f32_e32 v147, v189, v148
	v_and_b32_e32 v148, 0xffff0000, v15
	s_waitcnt lgkmcnt(12)
	v_fmac_f32_e32 v147, v190, v148
	v_lshlrev_b32_e32 v148, 16, v16
	s_waitcnt lgkmcnt(11)
	v_fmac_f32_e32 v147, v191, v148
	v_and_b32_e32 v148, 0xffff0000, v16
	s_waitcnt lgkmcnt(10)
	v_fmac_f32_e32 v147, v192, v148
	v_lshlrev_b32_e32 v148, 16, v17
	s_waitcnt lgkmcnt(9)
	v_fmac_f32_e32 v147, v193, v148
	v_and_b32_e32 v148, 0xffff0000, v17
	s_waitcnt lgkmcnt(8)
	v_fmac_f32_e32 v147, v194, v148
	v_lshlrev_b32_e32 v148, 16, v6
	s_waitcnt lgkmcnt(7)
	v_fmac_f32_e32 v147, v195, v148
	v_and_b32_e32 v148, 0xffff0000, v6
	s_waitcnt lgkmcnt(6)
	v_fmac_f32_e32 v147, v196, v148
	v_lshlrev_b32_e32 v148, 16, v7
	s_waitcnt lgkmcnt(5)
	v_fmac_f32_e32 v147, v197, v148
	v_and_b32_e32 v148, 0xffff0000, v7
	s_waitcnt lgkmcnt(4)
	v_fmac_f32_e32 v147, v198, v148
	v_lshlrev_b32_e32 v148, 16, v8
	s_waitcnt lgkmcnt(3)
	v_fmac_f32_e32 v147, v199, v148
	v_and_b32_e32 v148, 0xffff0000, v8
	s_waitcnt lgkmcnt(2)
	v_fmac_f32_e32 v147, v200, v148
	v_lshlrev_b32_e32 v148, 16, v9
	v_fma_f32 v139, v139, v140, 0
	v_fmac_f32_e32 v139, v141, v142
	v_fmac_f32_e32 v139, v143, v144
	s_waitcnt lgkmcnt(1)
	v_fmac_f32_e32 v147, v201, v148
	v_and_b32_e32 v148, 0xffff0000, v9
	v_fmac_f32_e32 v139, v145, v146
	s_waitcnt lgkmcnt(0)
	v_fmac_f32_e32 v147, v202, v148
	v_mul_f32_e64 v141, |v147|, s48
	v_exp_f32_e32 v141, v141
	v_min_f32_e32 v140, 0, v147
	v_add_f32_e32 v141, 1.0, v141
	v_cmp_gt_f32_e32 vcc, s68, v141
	s_nop 1
	v_cndmask_b32_e64 v142, 0, 32, vcc
	v_ldexp_f32 v141, v141, v142
	v_log_f32_e32 v141, v141
	s_nop 0
	v_mul_f32_e32 v142, 0x3f317217, v141
	v_fma_f32 v142, v141, s42, -v142
	v_fmac_f32_e32 v142, 0x3377d1cf, v141
	v_fmac_f32_e32 v142, 0x3f317217, v141
	v_cmp_lt_f32_e64 s[0:1], |v141|, s78
	s_nop 1
	v_cndmask_b32_e64 v141, v141, v142, s[0:1]
	v_cndmask_b32_e32 v142, 0, v164, vcc
	v_sub_f32_e32 v141, v141, v142
	v_sub_f32_e32 v140, v140, v141
	v_mul_f32_e32 v141, 0xbfb8aa3b, v139
	v_exp_f32_e32 v141, v141
	v_mul_f32_e32 v140, 0x3d800000, v140
	v_mul_f32_e32 v140, 0x3fb8aa3b, v140
	v_exp_f32_e32 v140, v140
	v_add_f32_e32 v141, 1.0, v141
	v_rcp_f32_e32 v141, v141
	s_nop 0
	v_mul_f32_e32 v139, v139, v141
	ds_write2st64_b32 v34, v140, v139 offset0:32 offset1:64
.LBB0_650:
	s_or_b64 exec, exec, s[24:25]
	s_and_saveexec_b64 s[24:25], s[12:13]
	s_cbranch_execz .LBB0_652
	ds_read_b32 v139, v90
	ds_read_b32 v147, v93
	ds_read_b32 v141, v91
	ds_read_b32 v149, v94
	s_waitcnt vmcnt(0)
	v_lshlrev_b32_e32 v148, 16, v10
	ds_read_b32 v143, v89
	ds_read_b32 v145, v87
	v_lshlrev_b32_e32 v140, 16, v48
	ds_read_b32 v188, v92
	ds_read_b32 v189, v88
	ds_read_b32 v190, v86
	ds_read_b32 v191, v84
	ds_read_b32 v192, v83
	ds_read_b32 v193, v82
	ds_read_b32 v194, v81
	ds_read_b32 v195, v80
	ds_read_b32 v196, v79
	s_waitcnt lgkmcnt(9)
	ds_read_b32 v197, v77
	ds_read_b32 v198, v76
	ds_read_b32 v199, v75
	ds_read_b32 v200, v74
	ds_read_b32 v201, v73
	ds_read_b32 v202, v72
	v_fmac_f32_e32 v147, v149, v148
	v_and_b32_e32 v148, 0xffff0000, v10
	v_lshlrev_b32_e32 v142, 16, v31
	v_lshlrev_b32_e32 v144, 16, v51
	v_lshlrev_b32_e32 v146, 16, v0
	s_waitcnt lgkmcnt(14)
	v_fmac_f32_e32 v147, v188, v148
	v_lshlrev_b32_e32 v148, 16, v11
	s_waitcnt lgkmcnt(13)
	v_fmac_f32_e32 v147, v189, v148
	v_and_b32_e32 v148, 0xffff0000, v11
	s_waitcnt lgkmcnt(12)
	v_fmac_f32_e32 v147, v190, v148
	v_lshlrev_b32_e32 v148, 16, v12
	s_waitcnt lgkmcnt(11)
	v_fmac_f32_e32 v147, v191, v148
	v_and_b32_e32 v148, 0xffff0000, v12
	s_waitcnt lgkmcnt(10)
	v_fmac_f32_e32 v147, v192, v148
	v_lshlrev_b32_e32 v148, 16, v13
	s_waitcnt lgkmcnt(9)
	v_fmac_f32_e32 v147, v193, v148
	v_and_b32_e32 v148, 0xffff0000, v13
	s_waitcnt lgkmcnt(8)
	v_fmac_f32_e32 v147, v194, v148
	v_lshlrev_b32_e32 v148, 16, v2
	s_waitcnt lgkmcnt(7)
	v_fmac_f32_e32 v147, v195, v148
	v_and_b32_e32 v148, 0xffff0000, v2
	s_waitcnt lgkmcnt(6)
	v_fmac_f32_e32 v147, v196, v148
	v_lshlrev_b32_e32 v148, 16, v3
	s_waitcnt lgkmcnt(5)
	v_fmac_f32_e32 v147, v197, v148
	v_and_b32_e32 v148, 0xffff0000, v3
	s_waitcnt lgkmcnt(4)
	v_fmac_f32_e32 v147, v198, v148
	v_lshlrev_b32_e32 v148, 16, v4
	s_waitcnt lgkmcnt(3)
	v_fmac_f32_e32 v147, v199, v148
	v_and_b32_e32 v148, 0xffff0000, v4
	v_fma_f32 v139, v139, v140, 0
	v_fmac_f32_e32 v139, v141, v142
	s_waitcnt lgkmcnt(2)
	v_fmac_f32_e32 v147, v200, v148
	v_lshlrev_b32_e32 v148, 16, v5
	v_fmac_f32_e32 v139, v143, v144
	s_waitcnt lgkmcnt(1)
	v_fmac_f32_e32 v147, v201, v148
	v_and_b32_e32 v148, 0xffff0000, v5
	v_fmac_f32_e32 v139, v145, v146
	s_waitcnt lgkmcnt(0)
	v_fmac_f32_e32 v147, v202, v148
	v_mul_f32_e64 v141, |v147|, s48
	v_exp_f32_e32 v141, v141
	v_min_f32_e32 v140, 0, v147
	v_add_f32_e32 v141, 1.0, v141
	v_cmp_gt_f32_e32 vcc, s68, v141
	s_nop 1
	v_cndmask_b32_e64 v142, 0, 32, vcc
	v_ldexp_f32 v141, v141, v142
	v_log_f32_e32 v141, v141
	s_nop 0
	v_mul_f32_e32 v142, 0x3f317217, v141
	v_fma_f32 v142, v141, s42, -v142
	v_fmac_f32_e32 v142, 0x3377d1cf, v141
	v_fmac_f32_e32 v142, 0x3f317217, v141
	v_cmp_lt_f32_e64 s[0:1], |v141|, s78
	s_nop 1
	v_cndmask_b32_e64 v141, v141, v142, s[0:1]
	v_cndmask_b32_e32 v142, 0, v164, vcc
	v_sub_f32_e32 v141, v141, v142
	v_sub_f32_e32 v140, v140, v141
	v_mul_f32_e32 v141, 0xbfb8aa3b, v139
	v_exp_f32_e32 v141, v141
	v_mul_f32_e32 v140, 0x3d800000, v140
	v_mul_f32_e32 v140, 0x3fb8aa3b, v140
	v_exp_f32_e32 v140, v140
	v_add_f32_e32 v141, 1.0, v141
	v_rcp_f32_e32 v141, v141
	s_nop 0
	v_mul_f32_e32 v139, v139, v141
	ds_write2st64_b32 v34, v140, v139 offset0:40 offset1:72
.LBB0_652:
	s_or_b64 exec, exec, s[24:25]
	ds_read_b32 v188, v54
	ds_read_b32 v189, v55
	ds_read_b32 v190, v56
	ds_read_b32 v191, v57
	ds_read_b32 v192, v58
	ds_read_b32 v193, v59
	ds_read_b32 v194, v60
	ds_read_b32 v195, v61
	ds_read_b32 v196, v62
	ds_read_b32 v197, v63
	ds_read_b32 v198, v64
	ds_read_b32 v199, v65
	s_waitcnt vmcnt(0)
	v_lshlrev_b32_e32 v95, 16, v95
	v_lshlrev_b32_e32 v85, 16, v85
	v_lshlrev_b32_e32 v98, 16, v98
	v_lshlrev_b32_e32 v96, 16, v96
	s_waitcnt lgkmcnt(11)
	v_fma_f32 v95, v188, v95, 0
	s_waitcnt lgkmcnt(10)
	v_fmac_f32_e32 v95, v189, v85
	s_waitcnt lgkmcnt(9)
	v_fmac_f32_e32 v95, v190, v98
	s_waitcnt lgkmcnt(8)
	v_fmac_f32_e32 v95, v191, v96
	v_mul_f32_e32 v85, 0xbfb8aa3b, v95
	v_exp_f32_e32 v85, v85
	v_lshlrev_b32_e32 v96, 16, v97
	v_add_f32_e32 v85, 1.0, v85
	v_rcp_f32_e32 v85, v85
	s_nop 0
	v_mul_f32_e32 v85, v95, v85
	ds_write_b32 v34, v85 offset:24576
	v_lshlrev_b32_e32 v95, 16, v99
	s_waitcnt lgkmcnt(8)
	v_fma_f32 v85, v192, v95, 0
	s_waitcnt lgkmcnt(7)
	v_fmac_f32_e32 v85, v193, v96
	v_lshlrev_b32_e32 v96, 16, v114
	s_waitcnt lgkmcnt(6)
	v_fmac_f32_e32 v85, v194, v96
	v_lshlrev_b32_e32 v96, 16, v100
	s_waitcnt lgkmcnt(5)
	v_fmac_f32_e32 v85, v195, v96
	v_mul_f32_e32 v95, 0xbfb8aa3b, v85
	v_exp_f32_e32 v95, v95
	v_lshlrev_b32_e32 v96, 16, v106
	v_add_f32_e32 v95, 1.0, v95
	v_rcp_f32_e32 v95, v95
	s_nop 0
	v_mul_f32_e32 v85, v85, v95
	ds_write_b32 v34, v85 offset:26624
	v_lshlrev_b32_e32 v95, 16, v107
	s_waitcnt lgkmcnt(5)
	v_fma_f32 v85, v196, v95, 0
	s_waitcnt lgkmcnt(4)
	v_fmac_f32_e32 v85, v197, v96
	v_lshlrev_b32_e32 v96, 16, v126
	s_waitcnt lgkmcnt(3)
	v_fmac_f32_e32 v85, v198, v96
	v_lshlrev_b32_e32 v96, 16, v109
	s_waitcnt lgkmcnt(2)
	v_fmac_f32_e32 v85, v199, v96
	v_mul_f32_e32 v95, 0xbfb8aa3b, v85
	v_exp_f32_e32 v95, v95
	s_nop 0
	v_add_f32_e32 v95, 1.0, v95
	v_rcp_f32_e32 v95, v95
	s_nop 0
	v_mul_f32_e32 v85, v85, v95
	ds_write_b32 v34, v85 offset:28672
	s_and_saveexec_b64 s[0:1], s[10:11]
	s_cbranch_execz .LBB0_662
	v_add_u32_e32 v7, s36, v137
	v_add_u32_e32 v6, 0x50, v7
	v_cmp_lt_i32_e32 vcc, 2, v6
	v_mov_b32_e32 v49, 0
	v_mov_b32_e32 v50, 0
	s_and_saveexec_b64 s[24:25], vcc
	s_cbranch_execz .LBB0_655
	v_add_u32_e32 v8, 0x4d, v7
	v_mad_u64_u32 v[8:9], s[38:39], v8, s69, v[36:37]
	global_load_ushort v50, v[8:9], off offset:384
